# v039 stack + SUV row-scale loads issued early in each token block
# speedup vs baseline: 1.0411x; 1.0071x over previous
.LBB0_32:
	s_andn2_saveexec_b64 s[0:1], s[0:1]
	v_mov_b32_e32 v69, s16
	v_add_f32_e32 v69, s10, v69
	v_add_f32_e32 v69, s11, v69
	s_or_b64 exec, exec, s[0:1]
	v_add_u32_e32 v59, 0x3000, v59
	v_cmp_ne_u32_e64 s[0:1], -1, v59
	v_readlane_b32 s10, v254, 10
	v_readlane_b32 s11, v254, 11
	v_cndmask_b32_e64 v70, 0, v59, s[0:1]
	v_add_f32_e32 v59, v68, v69
	v_cvt_u32_f32_e32 v59, v59
	v_mov_b32_e32 v72, s11
	v_cndmask_b32_e64 v71, 0, v72, s[0:1]
	v_add_u32_e32 v60, 0x3000, v60
	v_sub_u32_e32 v59, v59, v67
	v_add_u32_e32 v58, v59, v58
	ds_write_b32 v2, v59
	ds_write_b32 v4, v58
	v_add_u32_e32 v58, v58, v61
	ds_write_b32 v6, v58
	v_add_u32_e32 v58, v58, v62
	ds_write_b32 v8, v58
	v_add_u32_e32 v58, v58, v63
	ds_write_b32 v10, v58
	v_add_u32_e32 v58, v58, v64
	ds_write_b32 v12, v58
	v_add_u32_e32 v58, v58, v65
	ds_write_b32 v14, v58
	v_add_u32_e32 v58, v58, v66
	ds_write_b32 v16, v58
	s_waitcnt lgkmcnt(0)
	ds_read_b32 v58, v70
	v_cmp_ne_u32_e64 s[0:1], -1, v60
	s_waitcnt lgkmcnt(0)
	v_add_u32_e32 v62, v58, v39
	v_cndmask_b32_e64 v73, 0, v72, s[0:1]
	v_cndmask_b32_e64 v72, 0, v60, s[0:1]
	ds_read_b32 v39, v72
	s_waitcnt lgkmcnt(0)
	s_or_b32 s0, s40, 1
	s_ashr_i32 s1, s0, 31
	s_lshl_b64 s[42:43], s[0:1], 11
	s_waitcnt lgkmcnt(0)
	v_add_u32_e32 v63, v39, v37
	v_ashrrev_i32_e32 v37, 31, v36
	v_lshl_add_u64 v[58:59], v[36:37], 3, s[28:29]
	v_ashrrev_i32_e32 v39, 31, v38
	global_load_dwordx2 v[58:59], v[58:59], off
	v_lshl_add_u64 v[60:61], v[38:39], 3, s[28:29]
	global_load_dwordx2 v[60:61], v[60:61], off
	v_lshl_add_u32 v37, v62, 2, s93
	s_waitcnt vmcnt(1)
	v_mul_f32_e32 v39, v57, v59
	ds_write2st64_b32 v37, v36, v39 offset1:2
	ds_write_b32 v37, v58 offset:1024
	v_lshl_add_u32 v36, v63, 2, s93
	s_waitcnt vmcnt(0)
	v_mul_f32_e32 v37, v56, v61
	ds_write2st64_b32 v36, v38, v37 offset1:2
	ds_write_b32 v36, v60 offset:1024
	v_lshl_add_u64 v[56:57], v[18:19], 0, s[42:43]
	s_waitcnt vmcnt(0)
	v_mov_b32_e32 v36, v200
	v_mov_b32_e32 v37, v201
	v_mov_b32_e32 v38, v202
	v_mov_b32_e32 v39, v203
	v_mov_b32_e32 v60, v204
	v_mov_b32_e32 v61, v205
	v_mov_b32_e32 v62, v206
	v_mov_b32_e32 v63, v207
	v_lshlrev_b32_e32 v56, 16, v36
	v_lshlrev_b32_e32 v64, 16, v60
	v_and_b32_e32 v65, 0xffff0000, v60
	v_and_b32_e32 v57, 0xffff0000, v36
	v_lshlrev_b32_e32 v66, 16, v61
	v_and_b32_e32 v67, 0xffff0000, v61
	v_max3_f32 v36, |v64|, 0, |v65|
	v_lshlrev_b32_e32 v68, 16, v62
	v_and_b32_e32 v69, 0xffff0000, v62
	v_max3_f32 v36, v36, |v66|, |v67|
	v_lshlrev_b32_e32 v70, 16, v63
	v_and_b32_e32 v71, 0xffff0000, v63
	v_max3_f32 v36, v36, |v68|, |v69|
	v_max3_f32 v36, v36, |v70|, |v71|
	v_lshlrev_b32_e32 v58, 16, v37
	v_and_b32_e32 v59, 0xffff0000, v37
	v_max3_f32 v36, v36, |v56|, |v57|
	v_lshlrev_b32_e32 v60, 16, v38
	v_and_b32_e32 v61, 0xffff0000, v38
	v_max3_f32 v36, v36, |v58|, |v59|
	v_lshlrev_b32_e32 v62, 16, v39
	v_and_b32_e32 v63, 0xffff0000, v39
	v_max3_f32 v36, v36, |v60|, |v61|
	v_max3_f32 v36, v36, |v62|, |v63|
	s_nop 1
	v_mov_b32_dpp v37, v36 quad_perm:[1,0,3,2] row_mask:0xf bank_mask:0xf bound_ctrl:1
	v_max_f32_e32 v37, v37, v37
	v_max_f32_e32 v36, v36, v37
	s_nop 1
	v_mov_b32_dpp v37, v36 quad_perm:[2,3,0,1] row_mask:0xf bank_mask:0xf bound_ctrl:1
	v_max_f32_e32 v37, v37, v37
	v_max_f32_e32 v36, v36, v37
	s_nop 1
	v_mov_b32_dpp v37, v36 row_half_mirror row_mask:0xf bank_mask:0xf bound_ctrl:1
	v_max_f32_e32 v37, v37, v37
	v_max_f32_e32 v36, v36, v37
	s_nop 1
	v_mov_b32_dpp v37, v36 row_mirror row_mask:0xf bank_mask:0xf bound_ctrl:1
	v_max_f32_e32 v37, v37, v37
	v_max_f32_e32 v36, v36, v37
	s_nop 0
	v_readlane_b32 s10, v36, 32
	v_readlane_b32 s35, v36, 0
	v_readlane_b32 s37, v36, 16
	v_writelane_b32 v254, s10, 44
	v_writelane_b32 v254, s0, 46
	v_readlane_b32 s36, v36, 48
	s_nop 0
	v_writelane_b32 v254, s1, 47
	s_lshl_b64 s[0:1], s[0:1], 9
	v_lshl_or_b32 v72, v55, 2, s0
	v_mov_b32_e32 v73, s1
	v_lshl_add_u64 v[36:37], s[24:25], 0, v[72:73]
	v_or_b32_e32 v74, 0x100, v72
	v_mov_b32_e32 v75, s1
	v_mov_b32_e32 v36, v232
	v_lshl_add_u64 v[38:39], s[24:25], 0, v[74:75]
	v_mov_b32_e32 v38, v233
	v_lshl_add_u64 v[72:73], s[26:27], 0, v[72:73]
	v_mov_b32_e32 v72, v234
	v_lshl_add_u64 v[74:75], s[26:27], 0, v[74:75]
	v_mov_b32_e32 v73, v235
	v_lshlrev_b32_e32 v244, 3, v36
	global_load_dwordx2 v[240:241], v244, s[28:29]
	v_lshlrev_b32_e32 v245, 3, v38
	global_load_dwordx2 v[242:243], v245, s[28:29]
	v_add_u32_e32 v238, 0x1000, v236
	global_load_dwordx4 v[192:195], v238, s[98:99] offset:16
	global_load_dwordx4 v[196:199], v238, s[98:99]
	v_add_u32_e32 v239, 0x400, v237
	global_load_dword v228, v239, s[24:25]
	global_load_dword v229, v239, s[24:25] offset:256
	global_load_dword v230, v239, s[26:27]
	global_load_dword v231, v239, s[26:27] offset:256
	s_nop 0
	ds_write_b32 v20, v155
	ds_write_b32 v22, v155
	ds_write_b32 v24, v155
	ds_write_b32 v26, v155
	ds_write_b32 v28, v155
	ds_write_b32 v30, v155
	ds_write_b32 v32, v155
	ds_write_b32 v34, v155
	v_ashrrev_i32_e32 v37, 5, v36
	v_lshl_add_u32 v74, v37, 2, s93
	v_ashrrev_i32_e32 v39, 5, v38
	ds_add_rtn_u32 v37, v74, v208 offset:12288
	v_lshl_add_u32 v82, v39, 2, s93
	ds_add_rtn_u32 v39, v82, v208 offset:12288
	s_waitcnt lgkmcnt(0)
	ds_read_b32 v76, v2
	ds_read_b32 v75, v4
	ds_read_b32 v78, v6
	ds_read_b32 v77, v8
	s_waitcnt lgkmcnt(0)
	v_add_u32_e32 v79, v75, v76
	v_add3_u32 v81, v79, v78, v77
	ds_read_b32 v80, v10
	ds_read_b32 v79, v12
	s_waitcnt lgkmcnt(0)
	v_add3_u32 v83, v81, v80, v79
	ds_read_b32 v81, v14
	ds_read_b32 v84, v16
	s_waitcnt lgkmcnt(0)
	v_add3_u32 v83, v83, v81, v84
	v_cvt_f32_u32_e32 v84, v83
	s_nop 1
	v_add_f32_dpp v84, v84, v84 row_shr:1 row_mask:0xf bank_mask:0xf bound_ctrl:1
	s_nop 1
	v_add_f32_dpp v84, v84, v84 row_shr:2 row_mask:0xf bank_mask:0xf bound_ctrl:1
	s_nop 1
	v_add_f32_dpp v84, v84, v84 row_shr:4 row_mask:0xf bank_mask:0xf bound_ctrl:1
	s_nop 1
	v_add_f32_dpp v84, v84, v84 row_shr:8 row_mask:0xf bank_mask:0xf bound_ctrl:1
	s_nop 0
	v_readlane_b32 s10, v84, 15
	v_readlane_b32 s16, v84, 31
	v_readlane_b32 s11, v84, 47
	s_and_saveexec_b64 s[0:1], s[14:15]
	s_xor_b64 s[0:1], exec, s[0:1]
	s_cbranch_execz .LBB0_40
	s_and_saveexec_b64 s[18:19], s[12:13]
	s_xor_b64 s[46:47], exec, s[18:19]
	v_mov_b32_e32 v85, s10
	v_cndmask_b32_e32 v85, 0, v85, vcc
	s_andn2_saveexec_b64 s[46:47], s[46:47]
	v_mov_b32_e32 v85, s16
	v_add_f32_e32 v85, s10, v85
	s_or_b64 exec, exec, s[46:47]
.LBB0_40:
	s_andn2_saveexec_b64 s[0:1], s[0:1]
	v_mov_b32_e32 v85, s16
	v_add_f32_e32 v85, s10, v85
	v_add_f32_e32 v85, s11, v85
	s_or_b64 exec, exec, s[0:1]
	v_add_u32_e32 v74, 0x3000, v74
	v_cmp_ne_u32_e64 s[0:1], -1, v74
	v_readlane_b32 s10, v254, 10
	v_readlane_b32 s11, v254, 11
	v_cndmask_b32_e64 v86, 0, v74, s[0:1]
	v_add_f32_e32 v74, v84, v85
	v_cvt_u32_f32_e32 v74, v74
	v_mov_b32_e32 v88, s11
	v_cndmask_b32_e64 v87, 0, v88, s[0:1]
	v_add_u32_e32 v82, 0x3000, v82
	v_sub_u32_e32 v74, v74, v83
	ds_write_b32 v2, v74
	v_add_u32_e32 v74, v74, v76
	ds_write_b32 v4, v74
	v_add_u32_e32 v74, v74, v75
	ds_write_b32 v6, v74
	v_add_u32_e32 v74, v74, v78
	ds_write_b32 v8, v74
	v_add_u32_e32 v74, v74, v77
	ds_write_b32 v10, v74
	v_add_u32_e32 v74, v74, v80
	ds_write_b32 v12, v74
	v_add_u32_e32 v74, v74, v79
	ds_write_b32 v14, v74
	v_add_u32_e32 v74, v74, v81
	ds_write_b32 v16, v74
	s_waitcnt lgkmcnt(0)
	ds_read_b32 v74, v86
	v_cmp_ne_u32_e64 s[0:1], -1, v82
	s_waitcnt lgkmcnt(0)
	v_add_u32_e32 v78, v74, v37
	v_cndmask_b32_e64 v89, 0, v88, s[0:1]
	v_cndmask_b32_e64 v88, 0, v82, s[0:1]
	ds_read_b32 v37, v88
	s_waitcnt lgkmcnt(0)
	s_or_b32 s0, s40, 2
	s_ashr_i32 s1, s0, 31
	s_lshl_b64 s[46:47], s[0:1], 11
	v_writelane_b32 v254, s0, 48
	s_waitcnt lgkmcnt(0)
	v_add_u32_e32 v79, v37, v39
	v_ashrrev_i32_e32 v37, 31, v36
	v_lshl_add_u64 v[74:75], v[36:37], 3, s[28:29]
	v_ashrrev_i32_e32 v39, 31, v38
	s_waitcnt vmcnt(6)
	v_mov_b32_e32 v74, v240
	v_mov_b32_e32 v75, v241
	v_lshl_add_u64 v[76:77], v[38:39], 3, s[28:29]
	v_mov_b32_e32 v76, v242
	v_mov_b32_e32 v77, v243
	v_lshl_add_u32 v37, v78, 2, s93
	v_writelane_b32 v254, s1, 49
	s_lshl_b64 s[0:1], s[0:1], 9
	v_lshl_or_b32 v88, v55, 2, s0
	v_mov_b32_e32 v89, s1
	v_or_b32_e32 v90, 0x100, v88
	v_mov_b32_e32 v91, s1
	v_mul_f32_e32 v39, v72, v75
	ds_write2st64_b32 v37, v36, v39 offset0:6 offset1:8
	ds_write_b32 v37, v74 offset:2560
	v_lshl_add_u32 v36, v79, 2, s93
	v_mul_f32_e32 v37, v73, v77
	ds_write2st64_b32 v36, v38, v37 offset0:6 offset1:8
	ds_write_b32 v36, v76 offset:2560
	v_lshl_add_u64 v[72:73], v[18:19], 0, s[46:47]
	s_waitcnt vmcnt(0)
	v_mov_b32_e32 v36, v192
	v_mov_b32_e32 v37, v193
	v_mov_b32_e32 v38, v194
	v_mov_b32_e32 v39, v195
	v_mov_b32_e32 v76, v196
	v_mov_b32_e32 v77, v197
	v_mov_b32_e32 v78, v198
	v_mov_b32_e32 v79, v199
	v_lshlrev_b32_e32 v72, 16, v36
	v_lshlrev_b32_e32 v80, 16, v76
	v_and_b32_e32 v81, 0xffff0000, v76
	v_and_b32_e32 v73, 0xffff0000, v36
	v_lshlrev_b32_e32 v82, 16, v77
	v_and_b32_e32 v83, 0xffff0000, v77
	v_max3_f32 v36, |v80|, 0, |v81|
	v_lshlrev_b32_e32 v84, 16, v78
	v_and_b32_e32 v85, 0xffff0000, v78
	v_max3_f32 v36, v36, |v82|, |v83|
	v_lshlrev_b32_e32 v86, 16, v79
	v_and_b32_e32 v87, 0xffff0000, v79
	v_max3_f32 v36, v36, |v84|, |v85|
	v_max3_f32 v36, v36, |v86|, |v87|
	v_lshlrev_b32_e32 v74, 16, v37
	v_and_b32_e32 v75, 0xffff0000, v37
	v_max3_f32 v36, v36, |v72|, |v73|
	v_lshlrev_b32_e32 v76, 16, v38
	v_and_b32_e32 v77, 0xffff0000, v38
	v_max3_f32 v36, v36, |v74|, |v75|
	v_lshlrev_b32_e32 v78, 16, v39
	v_and_b32_e32 v79, 0xffff0000, v39
	v_max3_f32 v36, v36, |v76|, |v77|
	v_max3_f32 v36, v36, |v78|, |v79|
	v_lshl_add_u64 v[38:39], s[24:25], 0, v[90:91]
	v_mov_b32_e32 v38, v229
	v_mov_b32_dpp v37, v36 quad_perm:[1,0,3,2] row_mask:0xf bank_mask:0xf bound_ctrl:1
	v_max_f32_e32 v37, v37, v37
	v_max_f32_e32 v36, v36, v37
	v_lshl_add_u64 v[90:91], s[26:27], 0, v[90:91]
	s_nop 0
	v_mov_b32_dpp v37, v36 quad_perm:[2,3,0,1] row_mask:0xf bank_mask:0xf bound_ctrl:1
	v_max_f32_e32 v37, v37, v37
	v_max_f32_e32 v36, v36, v37
	s_nop 1
	v_mov_b32_dpp v37, v36 row_half_mirror row_mask:0xf bank_mask:0xf bound_ctrl:1
	v_max_f32_e32 v37, v37, v37
	v_max_f32_e32 v36, v36, v37
	s_nop 1
	v_mov_b32_dpp v37, v36 row_mirror row_mask:0xf bank_mask:0xf bound_ctrl:1
	v_max_f32_e32 v37, v37, v37
	v_max_f32_e32 v36, v36, v37
	s_nop 0
	v_readlane_b32 s74, v36, 0
	v_readlane_b32 s92, v36, 16
	v_readlane_b32 s90, v36, 32
	v_readlane_b32 s91, v36, 48
	v_lshl_add_u64 v[36:37], s[24:25], 0, v[88:89]
	v_mov_b32_e32 v36, v228
	v_lshl_add_u64 v[88:89], s[26:27], 0, v[88:89]
	v_mov_b32_e32 v88, v230
	s_waitcnt vmcnt(2)
	v_ashrrev_i32_e32 v39, 5, v38
	v_mov_b32_e32 v89, v231
	v_lshlrev_b32_e32 v244, 3, v36
	global_load_dwordx2 v[240:241], v244, s[28:29]
	v_lshlrev_b32_e32 v245, 3, v38
	global_load_dwordx2 v[242:243], v245, s[28:29]
	v_add_u32_e32 v238, 0x1800, v236
	global_load_dwordx4 v[200:203], v238, s[98:99] offset:16
	global_load_dwordx4 v[204:207], v238, s[98:99]
	v_add_u32_e32 v239, 0x600, v237
	global_load_dword v232, v239, s[24:25]
	global_load_dword v233, v239, s[24:25] offset:256
	global_load_dword v234, v239, s[26:27]
	global_load_dword v235, v239, s[26:27] offset:256
	s_nop 0
	ds_write_b32 v20, v155
	ds_write_b32 v22, v155
	ds_write_b32 v24, v155
	ds_write_b32 v26, v155
	ds_write_b32 v28, v155
	ds_write_b32 v30, v155
	ds_write_b32 v32, v155
	ds_write_b32 v34, v155
	v_lshl_add_u32 v98, v39, 2, s93
	v_ashrrev_i32_e32 v37, 5, v36
	v_lshl_add_u32 v90, v37, 2, s93
	ds_add_rtn_u32 v37, v90, v208 offset:12288
	ds_add_rtn_u32 v39, v98, v208 offset:12288
	s_waitcnt lgkmcnt(0)
	ds_read_b32 v92, v2
	ds_read_b32 v91, v4
	ds_read_b32 v94, v6
	ds_read_b32 v93, v8
	s_waitcnt lgkmcnt(0)
	v_add_u32_e32 v95, v91, v92
	v_add3_u32 v97, v95, v94, v93
	ds_read_b32 v96, v10
	ds_read_b32 v95, v12
	s_waitcnt lgkmcnt(0)
	v_add3_u32 v99, v97, v96, v95
	ds_read_b32 v97, v14
	ds_read_b32 v100, v16
	s_waitcnt lgkmcnt(0)
	v_add3_u32 v99, v99, v97, v100
	v_cvt_f32_u32_e32 v100, v99
	s_nop 1
	v_add_f32_dpp v100, v100, v100 row_shr:1 row_mask:0xf bank_mask:0xf bound_ctrl:1
	s_nop 1
	v_add_f32_dpp v100, v100, v100 row_shr:2 row_mask:0xf bank_mask:0xf bound_ctrl:1
	s_nop 1
	v_add_f32_dpp v100, v100, v100 row_shr:4 row_mask:0xf bank_mask:0xf bound_ctrl:1
	s_nop 1
	v_add_f32_dpp v100, v100, v100 row_shr:8 row_mask:0xf bank_mask:0xf bound_ctrl:1
	s_nop 0
	v_readlane_b32 s10, v100, 15
	v_readlane_b32 s16, v100, 31
	v_readlane_b32 s11, v100, 47
	s_and_saveexec_b64 s[0:1], s[14:15]
	s_xor_b64 s[0:1], exec, s[0:1]
	s_cbranch_execz .LBB0_48
	s_and_saveexec_b64 s[18:19], s[12:13]
	s_xor_b64 s[50:51], exec, s[18:19]
	v_mov_b32_e32 v101, s10
	v_cndmask_b32_e32 v101, 0, v101, vcc
	s_andn2_saveexec_b64 s[50:51], s[50:51]
	v_mov_b32_e32 v101, s16
	v_add_f32_e32 v101, s10, v101
	s_or_b64 exec, exec, s[50:51]
.LBB0_48:
	s_andn2_saveexec_b64 s[0:1], s[0:1]
	v_mov_b32_e32 v101, s16
	v_add_f32_e32 v101, s10, v101
	v_add_f32_e32 v101, s11, v101
	s_or_b64 exec, exec, s[0:1]
	v_add_u32_e32 v90, 0x3000, v90
	v_cmp_ne_u32_e64 s[0:1], -1, v90
	v_readlane_b32 s10, v254, 10
	v_readlane_b32 s11, v254, 11
	v_cndmask_b32_e64 v102, 0, v90, s[0:1]
	v_add_f32_e32 v90, v100, v101
	v_cvt_u32_f32_e32 v90, v90
	v_mov_b32_e32 v104, s11
	v_cndmask_b32_e64 v103, 0, v104, s[0:1]
	v_add_u32_e32 v98, 0x3000, v98
	v_sub_u32_e32 v90, v90, v99
	ds_write_b32 v2, v90
	v_add_u32_e32 v90, v90, v92
	ds_write_b32 v4, v90
	v_add_u32_e32 v90, v90, v91
	ds_write_b32 v6, v90
	v_add_u32_e32 v90, v90, v94
	ds_write_b32 v8, v90
	v_add_u32_e32 v90, v90, v93
	ds_write_b32 v10, v90
	v_add_u32_e32 v90, v90, v96
	ds_write_b32 v12, v90
	v_add_u32_e32 v90, v90, v95
	ds_write_b32 v14, v90
	v_add_u32_e32 v90, v90, v97
	ds_write_b32 v16, v90
	s_waitcnt lgkmcnt(0)
	ds_read_b32 v90, v102
	v_cmp_ne_u32_e64 s[0:1], -1, v98
	s_waitcnt lgkmcnt(0)
	v_add_u32_e32 v94, v90, v37
	v_cndmask_b32_e64 v105, 0, v104, s[0:1]
	v_cndmask_b32_e64 v104, 0, v98, s[0:1]
	ds_read_b32 v37, v104
	s_waitcnt lgkmcnt(0)
	s_or_b32 s0, s40, 3
	s_ashr_i32 s1, s0, 31
	s_lshl_b64 s[50:51], s[0:1], 11
	v_writelane_b32 v254, s0, 50
	s_waitcnt lgkmcnt(0)
	v_add_u32_e32 v95, v37, v39
	v_ashrrev_i32_e32 v37, 31, v36
	v_lshl_add_u64 v[90:91], v[36:37], 3, s[28:29]
	v_ashrrev_i32_e32 v39, 31, v38
	s_waitcnt vmcnt(6)
	v_mov_b32_e32 v90, v240
	v_mov_b32_e32 v91, v241
	v_lshl_add_u64 v[92:93], v[38:39], 3, s[28:29]
	v_mov_b32_e32 v92, v242
	v_mov_b32_e32 v93, v243
	v_lshl_add_u32 v37, v94, 2, s93
	v_writelane_b32 v254, s1, 51
	s_lshl_b64 s[0:1], s[0:1], 9
	v_lshl_or_b32 v94, v55, 2, s0
	v_or_b32_e32 v96, 0x100, v94
	v_mov_b32_e32 v97, s1
	v_mul_f32_e32 v39, v88, v91
	ds_write2st64_b32 v37, v36, v39 offset0:12 offset1:14
	ds_write_b32 v37, v90 offset:4096
	v_lshl_add_u32 v36, v95, 2, s93
	v_mul_f32_e32 v37, v89, v93
	ds_write2st64_b32 v36, v38, v37 offset0:12 offset1:14
	ds_write_b32 v36, v92 offset:4096
	v_lshl_add_u64 v[88:89], v[18:19], 0, s[50:51]
	s_waitcnt vmcnt(0)
	v_mov_b32_e32 v36, v200
	v_mov_b32_e32 v37, v201
	v_mov_b32_e32 v38, v202
	v_mov_b32_e32 v39, v203
	v_mov_b32_e32 v90, v204
	v_mov_b32_e32 v91, v205
	v_mov_b32_e32 v92, v206
	v_mov_b32_e32 v93, v207
	v_mov_b32_e32 v95, s1
	v_lshlrev_b32_e32 v112, 16, v36
	v_lshlrev_b32_e32 v110, 16, v90
	v_and_b32_e32 v119, 0xffff0000, v90
	v_and_b32_e32 v113, 0xffff0000, v36
	v_lshlrev_b32_e32 v111, 16, v91
	v_and_b32_e32 v114, 0xffff0000, v91
	v_max3_f32 v36, |v110|, 0, |v119|
	v_lshlrev_b32_e32 v115, 16, v92
	v_and_b32_e32 v116, 0xffff0000, v92
	v_max3_f32 v36, v36, |v111|, |v114|
	v_lshlrev_b32_e32 v117, 16, v93
	v_and_b32_e32 v118, 0xffff0000, v93
	v_max3_f32 v36, v36, |v115|, |v116|
	v_max3_f32 v36, v36, |v117|, |v118|
	v_lshlrev_b32_e32 v88, 16, v37
	v_and_b32_e32 v89, 0xffff0000, v37
	v_max3_f32 v36, v36, |v112|, |v113|
	v_lshlrev_b32_e32 v90, 16, v38
	v_and_b32_e32 v91, 0xffff0000, v38
	v_max3_f32 v36, v36, |v88|, |v89|
	v_lshlrev_b32_e32 v92, 16, v39
	v_and_b32_e32 v93, 0xffff0000, v39
	v_max3_f32 v36, v36, |v90|, |v91|
	v_max3_f32 v36, v36, |v92|, |v93|
	v_lshl_add_u64 v[38:39], s[24:25], 0, v[96:97]
	v_mov_b32_e32 v38, v233
	v_mov_b32_dpp v37, v36 quad_perm:[1,0,3,2] row_mask:0xf bank_mask:0xf bound_ctrl:1
	v_max_f32_e32 v37, v37, v37
	v_max_f32_e32 v36, v36, v37
	v_lshl_add_u64 v[96:97], s[26:27], 0, v[96:97]
	s_nop 0
	v_mov_b32_dpp v37, v36 quad_perm:[2,3,0,1] row_mask:0xf bank_mask:0xf bound_ctrl:1
	v_max_f32_e32 v37, v37, v37
	v_max_f32_e32 v36, v36, v37
	s_nop 1
	v_mov_b32_dpp v37, v36 row_half_mirror row_mask:0xf bank_mask:0xf bound_ctrl:1
	v_max_f32_e32 v37, v37, v37
	v_max_f32_e32 v36, v36, v37
	s_nop 1
	v_mov_b32_dpp v37, v36 row_mirror row_mask:0xf bank_mask:0xf bound_ctrl:1
	v_max_f32_e32 v37, v37, v37
	v_max_f32_e32 v36, v36, v37
	s_nop 0
	v_readlane_b32 s20, v36, 0
	v_readlane_b32 s30, v36, 16
	v_readlane_b32 s97, v36, 32
	v_readlane_b32 s21, v36, 48
	v_lshl_add_u64 v[36:37], s[24:25], 0, v[94:95]
	v_mov_b32_e32 v36, v232
	v_lshl_add_u64 v[94:95], s[26:27], 0, v[94:95]
	v_mov_b32_e32 v94, v234
	s_waitcnt vmcnt(2)
	v_ashrrev_i32_e32 v39, 5, v38
	v_mov_b32_e32 v95, v235
	v_lshlrev_b32_e32 v244, 3, v36
	global_load_dwordx2 v[240:241], v244, s[28:29]
	v_lshlrev_b32_e32 v245, 3, v38
	global_load_dwordx2 v[242:243], v245, s[28:29]
	v_add_u32_e32 v238, 0x2000, v236
	global_load_dwordx4 v[192:195], v238, s[98:99] offset:16
	global_load_dwordx4 v[196:199], v238, s[98:99]
	v_add_u32_e32 v239, 0x800, v237
	global_load_dword v228, v239, s[24:25]
	global_load_dword v229, v239, s[24:25] offset:256
	global_load_dword v230, v239, s[26:27]
	global_load_dword v231, v239, s[26:27] offset:256
	s_nop 0
	ds_write_b32 v20, v155
	ds_write_b32 v22, v155
	ds_write_b32 v24, v155
	ds_write_b32 v26, v155
	ds_write_b32 v28, v155
	ds_write_b32 v30, v155
	ds_write_b32 v32, v155
	ds_write_b32 v34, v155
	v_lshl_add_u32 v104, v39, 2, s93
	v_ashrrev_i32_e32 v37, 5, v36
	v_lshl_add_u32 v96, v37, 2, s93
	ds_add_rtn_u32 v37, v96, v208 offset:12288
	ds_add_rtn_u32 v39, v104, v208 offset:12288
	s_waitcnt lgkmcnt(0)
	ds_read_b32 v98, v2
	ds_read_b32 v97, v4
	ds_read_b32 v100, v6
	ds_read_b32 v99, v8
	s_waitcnt lgkmcnt(0)
	v_add_u32_e32 v101, v97, v98
	v_add3_u32 v103, v101, v100, v99
	ds_read_b32 v102, v10
	ds_read_b32 v101, v12
	s_waitcnt lgkmcnt(0)
	v_add3_u32 v105, v103, v102, v101
	ds_read_b32 v103, v14
	ds_read_b32 v106, v16
	s_waitcnt lgkmcnt(0)
	v_add3_u32 v105, v105, v103, v106
	v_cvt_f32_u32_e32 v106, v105
	s_nop 1
	v_add_f32_dpp v106, v106, v106 row_shr:1 row_mask:0xf bank_mask:0xf bound_ctrl:1
	s_nop 1
	v_add_f32_dpp v106, v106, v106 row_shr:2 row_mask:0xf bank_mask:0xf bound_ctrl:1
	s_nop 1
	v_add_f32_dpp v106, v106, v106 row_shr:4 row_mask:0xf bank_mask:0xf bound_ctrl:1
	s_nop 1
	v_add_f32_dpp v106, v106, v106 row_shr:8 row_mask:0xf bank_mask:0xf bound_ctrl:1
	s_nop 0
	v_readlane_b32 s10, v106, 15
	v_readlane_b32 s16, v106, 31
	v_readlane_b32 s11, v106, 47
	s_and_saveexec_b64 s[0:1], s[14:15]
	s_xor_b64 s[0:1], exec, s[0:1]
	s_cbranch_execz .LBB0_56
	s_and_saveexec_b64 s[18:19], s[12:13]
	s_xor_b64 s[54:55], exec, s[18:19]
	v_mov_b32_e32 v107, s10
	v_cndmask_b32_e32 v107, 0, v107, vcc
	s_andn2_saveexec_b64 s[54:55], s[54:55]
	v_mov_b32_e32 v107, s16
	v_add_f32_e32 v107, s10, v107
	s_or_b64 exec, exec, s[54:55]
.LBB0_56:
	s_andn2_saveexec_b64 s[0:1], s[0:1]
	v_mov_b32_e32 v107, s16
	v_add_f32_e32 v107, s10, v107
	v_add_f32_e32 v107, s11, v107
	s_or_b64 exec, exec, s[0:1]
	v_add_u32_e32 v96, 0x3000, v96
	v_cmp_ne_u32_e64 s[0:1], -1, v96
	v_readlane_b32 s10, v254, 10
	v_readlane_b32 s11, v254, 11
	v_cndmask_b32_e64 v108, 0, v96, s[0:1]
	v_add_f32_e32 v96, v106, v107
	v_cvt_u32_f32_e32 v96, v96
	v_mov_b32_e32 v120, s11
	v_cndmask_b32_e64 v109, 0, v120, s[0:1]
	v_add_u32_e32 v104, 0x3000, v104
	v_sub_u32_e32 v96, v96, v105
	ds_write_b32 v2, v96
	v_add_u32_e32 v96, v96, v98
	ds_write_b32 v4, v96
	v_add_u32_e32 v96, v96, v97
	ds_write_b32 v6, v96
	v_add_u32_e32 v96, v96, v100
	ds_write_b32 v8, v96
	v_add_u32_e32 v96, v96, v99
	ds_write_b32 v10, v96
	v_add_u32_e32 v96, v96, v102
	ds_write_b32 v12, v96
	v_add_u32_e32 v96, v96, v101
	ds_write_b32 v14, v96
	v_add_u32_e32 v96, v96, v103
	ds_write_b32 v16, v96
	s_waitcnt lgkmcnt(0)
	ds_read_b32 v96, v108
	v_cmp_ne_u32_e64 s[0:1], -1, v104
	s_waitcnt lgkmcnt(0)
	v_add_u32_e32 v100, v96, v37
	v_cndmask_b32_e64 v121, 0, v120, s[0:1]
	v_cndmask_b32_e64 v120, 0, v104, s[0:1]
	ds_read_b32 v37, v120
	s_waitcnt lgkmcnt(0)
	s_or_b32 s0, s40, 4
	s_ashr_i32 s1, s0, 31
	s_lshl_b64 s[54:55], s[0:1], 11
	v_writelane_b32 v254, s0, 52
	s_waitcnt lgkmcnt(0)
	v_add_u32_e32 v101, v37, v39
	v_ashrrev_i32_e32 v37, 31, v36
	v_lshl_add_u64 v[96:97], v[36:37], 3, s[28:29]
	v_ashrrev_i32_e32 v39, 31, v38
	s_waitcnt vmcnt(6)
	v_mov_b32_e32 v96, v240
	v_mov_b32_e32 v97, v241
	v_lshl_add_u64 v[98:99], v[38:39], 3, s[28:29]
	v_mov_b32_e32 v98, v242
	v_mov_b32_e32 v99, v243
	v_lshl_add_u32 v37, v100, 2, s93
	v_writelane_b32 v254, s1, 53
	s_lshl_b64 s[0:1], s[0:1], 9
	v_mul_f32_e32 v39, v94, v97
	ds_write2st64_b32 v37, v36, v39 offset0:18 offset1:20
	ds_write_b32 v37, v96 offset:5632
	v_lshl_add_u32 v36, v101, 2, s93
	v_mul_f32_e32 v37, v95, v99
	ds_write2st64_b32 v36, v38, v37 offset0:18 offset1:20
	ds_write_b32 v36, v98 offset:5632
	v_lshl_add_u64 v[94:95], v[18:19], 0, s[54:55]
	s_waitcnt vmcnt(0)
	v_mov_b32_e32 v36, v192
	v_mov_b32_e32 v37, v193
	v_mov_b32_e32 v38, v194
	v_mov_b32_e32 v39, v195
	s_nop 0
	v_mov_b32_e32 v94, v196
	v_mov_b32_e32 v95, v197
	v_mov_b32_e32 v96, v198
	v_mov_b32_e32 v97, v199
	v_lshlrev_b32_e32 v108, 16, v36
	v_lshlrev_b32_e32 v106, 16, v94
	v_and_b32_e32 v141, 0xffff0000, v94
	v_and_b32_e32 v125, 0xffff0000, v36
	v_lshlrev_b32_e32 v107, 16, v95
	v_and_b32_e32 v126, 0xffff0000, v95
	v_max3_f32 v36, |v106|, 0, |v141|
	v_lshlrev_b32_e32 v127, 16, v96
	v_and_b32_e32 v138, 0xffff0000, v96
	v_max3_f32 v36, v36, |v107|, |v126|
	v_lshlrev_b32_e32 v139, 16, v97
	v_and_b32_e32 v140, 0xffff0000, v97
	v_max3_f32 v36, v36, |v127|, |v138|
	v_max3_f32 v36, v36, |v139|, |v140|
	v_lshlrev_b32_e32 v109, 16, v37
	v_and_b32_e32 v120, 0xffff0000, v37
	v_max3_f32 v36, v36, |v108|, |v125|
	v_lshlrev_b32_e32 v121, 16, v38
	v_and_b32_e32 v122, 0xffff0000, v38
	v_max3_f32 v36, v36, |v109|, |v120|
	v_lshlrev_b32_e32 v123, 16, v39
	v_and_b32_e32 v124, 0xffff0000, v39
	v_max3_f32 v36, v36, |v121|, |v122|
	v_max3_f32 v36, v36, |v123|, |v124|
	v_lshl_or_b32 v94, v55, 2, s0
	v_mov_b32_e32 v95, s1
	v_mov_b32_dpp v37, v36 quad_perm:[1,0,3,2] row_mask:0xf bank_mask:0xf bound_ctrl:1
	v_max_f32_e32 v37, v37, v37
	v_max_f32_e32 v36, v36, v37
	v_or_b32_e32 v96, 0x100, v94
	v_mov_b32_e32 v97, s1
	v_mov_b32_dpp v37, v36 quad_perm:[2,3,0,1] row_mask:0xf bank_mask:0xf bound_ctrl:1
	v_max_f32_e32 v37, v37, v37
	v_max_f32_e32 v36, v36, v37
	v_lshl_add_u64 v[38:39], s[24:25], 0, v[96:97]
	v_mov_b32_e32 v38, v229
	v_mov_b32_dpp v37, v36 row_half_mirror row_mask:0xf bank_mask:0xf bound_ctrl:1
	v_max_f32_e32 v37, v37, v37
	v_max_f32_e32 v36, v36, v37
	v_lshl_add_u64 v[96:97], s[26:27], 0, v[96:97]
	s_nop 0
	v_mov_b32_dpp v37, v36 row_mirror row_mask:0xf bank_mask:0xf bound_ctrl:1
	v_max_f32_e32 v37, v37, v37
	v_max_f32_e32 v36, v36, v37
	s_nop 0
	v_readlane_b32 s10, v36, 0
	v_readlane_b32 s16, v36, 16
	v_readlane_b32 s31, v36, 32
	v_readlane_b32 s11, v36, 48
	v_lshl_add_u64 v[36:37], s[24:25], 0, v[94:95]
	v_mov_b32_e32 v36, v228
	v_lshl_add_u64 v[94:95], s[26:27], 0, v[94:95]
	v_mov_b32_e32 v94, v230
	s_waitcnt vmcnt(2)
	v_ashrrev_i32_e32 v39, 5, v38
	v_mov_b32_e32 v95, v231
	v_lshlrev_b32_e32 v244, 3, v36
	global_load_dwordx2 v[240:241], v244, s[28:29]
	v_lshlrev_b32_e32 v245, 3, v38
	global_load_dwordx2 v[242:243], v245, s[28:29]
	v_add_u32_e32 v238, 0x2800, v236
	global_load_dwordx4 v[200:203], v238, s[98:99] offset:16
	global_load_dwordx4 v[204:207], v238, s[98:99]
	v_add_u32_e32 v239, 0xa00, v237
	global_load_dword v232, v239, s[24:25]
	global_load_dword v233, v239, s[24:25] offset:256
	global_load_dword v234, v239, s[26:27]
	global_load_dword v235, v239, s[26:27] offset:256
	s_nop 0
	ds_write_b32 v20, v155
	ds_write_b32 v22, v155
	ds_write_b32 v24, v155
	ds_write_b32 v26, v155
	ds_write_b32 v28, v155
	ds_write_b32 v30, v155
	ds_write_b32 v32, v155
	ds_write_b32 v34, v155
	v_lshl_add_u32 v104, v39, 2, s93
	v_ashrrev_i32_e32 v37, 5, v36
	v_lshl_add_u32 v96, v37, 2, s93
	ds_add_rtn_u32 v37, v96, v208 offset:12288
	ds_add_rtn_u32 v39, v104, v208 offset:12288
	s_waitcnt lgkmcnt(0)
	ds_read_b32 v98, v2
	ds_read_b32 v97, v4
	ds_read_b32 v100, v6
	ds_read_b32 v99, v8
	s_waitcnt lgkmcnt(0)
	v_add_u32_e32 v101, v97, v98
	v_add3_u32 v103, v101, v100, v99
	ds_read_b32 v102, v10
	ds_read_b32 v101, v12
	s_waitcnt lgkmcnt(0)
	v_add3_u32 v105, v103, v102, v101
	ds_read_b32 v103, v14
	ds_read_b32 v128, v16
	s_waitcnt lgkmcnt(0)
	v_add3_u32 v105, v105, v103, v128
	v_cvt_f32_u32_e32 v128, v105
	s_nop 1
	v_add_f32_dpp v128, v128, v128 row_shr:1 row_mask:0xf bank_mask:0xf bound_ctrl:1
	s_nop 1
	v_add_f32_dpp v128, v128, v128 row_shr:2 row_mask:0xf bank_mask:0xf bound_ctrl:1
	s_nop 1
	v_add_f32_dpp v128, v128, v128 row_shr:4 row_mask:0xf bank_mask:0xf bound_ctrl:1
	s_nop 1
	v_add_f32_dpp v128, v128, v128 row_shr:8 row_mask:0xf bank_mask:0xf bound_ctrl:1
	s_nop 0
	v_readlane_b32 s17, v128, 15
	v_readlane_b32 s19, v128, 31
	v_readlane_b32 s18, v128, 47
	s_and_saveexec_b64 s[0:1], s[14:15]
	s_xor_b64 s[0:1], exec, s[0:1]
	s_cbranch_execz .LBB0_64
	s_and_saveexec_b64 s[44:45], s[12:13]
	s_xor_b64 s[58:59], exec, s[44:45]
	v_mov_b32_e32 v129, s17
	v_cndmask_b32_e32 v129, 0, v129, vcc
	s_andn2_saveexec_b64 s[58:59], s[58:59]
	v_mov_b32_e32 v129, s19
	v_add_f32_e32 v129, s17, v129
	s_or_b64 exec, exec, s[58:59]
.LBB0_64:
	s_andn2_saveexec_b64 s[0:1], s[0:1]
	v_mov_b32_e32 v129, s19
	v_add_f32_e32 v129, s17, v129
	v_add_f32_e32 v129, s18, v129
	s_or_b64 exec, exec, s[0:1]
	v_add_u32_e32 v96, 0x3000, v96
	v_cmp_ne_u32_e64 s[0:1], -1, v96
	v_readlane_b32 s18, v254, 10
	v_readlane_b32 s19, v254, 11
	v_cndmask_b32_e64 v136, 0, v96, s[0:1]
	v_add_f32_e32 v96, v128, v129
	v_cvt_u32_f32_e32 v96, v96
	v_mov_b32_e32 v142, s19
	v_cndmask_b32_e64 v137, 0, v142, s[0:1]
	v_add_u32_e32 v104, 0x3000, v104
	v_sub_u32_e32 v96, v96, v105
	ds_write_b32 v2, v96
	v_add_u32_e32 v96, v96, v98
	ds_write_b32 v4, v96
	v_add_u32_e32 v96, v96, v97
	ds_write_b32 v6, v96
	v_add_u32_e32 v96, v96, v100
	ds_write_b32 v8, v96
	v_add_u32_e32 v96, v96, v99
	ds_write_b32 v10, v96
	v_add_u32_e32 v96, v96, v102
	ds_write_b32 v12, v96
	v_add_u32_e32 v96, v96, v101
	ds_write_b32 v14, v96
	v_add_u32_e32 v96, v96, v103
	ds_write_b32 v16, v96
	s_waitcnt lgkmcnt(0)
	ds_read_b32 v96, v136
	v_cmp_ne_u32_e64 s[0:1], -1, v104
	s_or_b32 s62, s40, 5
	s_ashr_i32 s63, s62, 31
	v_cndmask_b32_e64 v143, 0, v142, s[0:1]
	v_cndmask_b32_e64 v142, 0, v104, s[0:1]
	s_lshl_b64 s[58:59], s[62:63], 11
	s_lshl_b64 s[0:1], s[62:63], 9
	s_waitcnt lgkmcnt(0)
	v_add_u32_e32 v100, v96, v37
	ds_read_b32 v37, v142
	s_waitcnt lgkmcnt(0)
	s_waitcnt lgkmcnt(0)
	v_add_u32_e32 v101, v37, v39
	v_ashrrev_i32_e32 v37, 31, v36
	v_lshl_add_u64 v[96:97], v[36:37], 3, s[28:29]
	v_ashrrev_i32_e32 v39, 31, v38
	s_waitcnt vmcnt(6)
	v_mov_b32_e32 v96, v240
	v_mov_b32_e32 v97, v241
	v_lshl_add_u64 v[98:99], v[38:39], 3, s[28:29]
	v_mov_b32_e32 v98, v242
	v_mov_b32_e32 v99, v243
	v_lshl_add_u32 v37, v100, 2, s93
	v_mul_f32_e32 v39, v94, v97
	ds_write2st64_b32 v37, v36, v39 offset0:24 offset1:26
	ds_write_b32 v37, v96 offset:7168
	v_lshl_add_u32 v36, v101, 2, s93
	v_mul_f32_e32 v37, v95, v99
	ds_write2st64_b32 v36, v38, v37 offset0:24 offset1:26
	ds_write_b32 v36, v98 offset:7168
	v_lshl_add_u64 v[94:95], v[18:19], 0, s[58:59]
	s_waitcnt vmcnt(0)
	v_mov_b32_e32 v36, v200
	v_mov_b32_e32 v37, v201
	v_mov_b32_e32 v38, v202
	v_mov_b32_e32 v39, v203
	s_nop 0
	v_mov_b32_e32 v94, v204
	v_mov_b32_e32 v95, v205
	v_mov_b32_e32 v96, v206
	v_mov_b32_e32 v97, v207
	v_lshlrev_b32_e32 v104, 16, v36
	v_lshlrev_b32_e32 v102, 16, v94
	v_and_b32_e32 v152, 0xffff0000, v94
	v_and_b32_e32 v146, 0xffff0000, v36
	v_lshlrev_b32_e32 v103, 16, v95
	v_and_b32_e32 v147, 0xffff0000, v95
	v_max3_f32 v36, |v102|, 0, |v152|
	v_lshlrev_b32_e32 v148, 16, v96
	v_and_b32_e32 v149, 0xffff0000, v96
	v_max3_f32 v36, v36, |v103|, |v147|
	v_lshlrev_b32_e32 v150, 16, v97
	v_and_b32_e32 v151, 0xffff0000, v97
	v_max3_f32 v36, v36, |v148|, |v149|
	v_max3_f32 v36, v36, |v150|, |v151|
	v_lshlrev_b32_e32 v105, 16, v37
	v_and_b32_e32 v137, 0xffff0000, v37
	v_max3_f32 v36, v36, |v104|, |v146|
	v_lshlrev_b32_e32 v142, 16, v38
	v_and_b32_e32 v143, 0xffff0000, v38
	v_max3_f32 v36, v36, |v105|, |v137|
	v_lshlrev_b32_e32 v144, 16, v39
	v_and_b32_e32 v145, 0xffff0000, v39
	v_max3_f32 v36, v36, |v142|, |v143|
	v_max3_f32 v36, v36, |v144|, |v145|
	v_lshl_or_b32 v94, v55, 2, s0
	v_mov_b32_e32 v95, s1
	v_mov_b32_dpp v37, v36 quad_perm:[1,0,3,2] row_mask:0xf bank_mask:0xf bound_ctrl:1
	v_max_f32_e32 v37, v37, v37
	v_max_f32_e32 v36, v36, v37
	v_or_b32_e32 v96, 0x100, v94
	v_mov_b32_e32 v97, s1
	v_mov_b32_dpp v37, v36 quad_perm:[2,3,0,1] row_mask:0xf bank_mask:0xf bound_ctrl:1
	v_max_f32_e32 v37, v37, v37
	v_max_f32_e32 v36, v36, v37
	v_lshl_add_u64 v[38:39], s[24:25], 0, v[96:97]
	v_mov_b32_e32 v38, v233
	v_mov_b32_dpp v37, v36 row_half_mirror row_mask:0xf bank_mask:0xf bound_ctrl:1
	v_max_f32_e32 v37, v37, v37
	v_max_f32_e32 v36, v36, v37
	v_lshl_add_u64 v[96:97], s[26:27], 0, v[96:97]
	s_nop 0
	v_mov_b32_dpp v37, v36 row_mirror row_mask:0xf bank_mask:0xf bound_ctrl:1
	v_max_f32_e32 v37, v37, v37
	v_max_f32_e32 v36, v36, v37
	s_nop 0
	v_readlane_b32 s75, v36, 0
	v_readlane_b32 s19, v36, 16
	v_readlane_b32 s17, v36, 32
	v_readlane_b32 s18, v36, 48
	v_lshl_add_u64 v[36:37], s[24:25], 0, v[94:95]
	v_mov_b32_e32 v36, v232
	v_lshl_add_u64 v[94:95], s[26:27], 0, v[94:95]
	v_mov_b32_e32 v94, v234
	s_waitcnt vmcnt(2)
	v_ashrrev_i32_e32 v39, 5, v38
	v_mov_b32_e32 v95, v235
	v_lshlrev_b32_e32 v244, 3, v36
	global_load_dwordx2 v[240:241], v244, s[28:29]
	v_lshlrev_b32_e32 v245, 3, v38
	global_load_dwordx2 v[242:243], v245, s[28:29]
	v_add_u32_e32 v238, 0x3000, v236
	global_load_dwordx4 v[192:195], v238, s[98:99] offset:16
	global_load_dwordx4 v[196:199], v238, s[98:99]
	v_add_u32_e32 v239, 0xc00, v237
	global_load_dword v228, v239, s[24:25]
	global_load_dword v229, v239, s[24:25] offset:256
	global_load_dword v230, v239, s[26:27]
	global_load_dword v231, v239, s[26:27] offset:256
	s_nop 0
	ds_write_b32 v20, v155
	ds_write_b32 v22, v155
	ds_write_b32 v24, v155
	ds_write_b32 v26, v155
	ds_write_b32 v28, v155
	ds_write_b32 v30, v155
	ds_write_b32 v32, v155
	ds_write_b32 v34, v155
	v_lshl_add_u32 v136, v39, 2, s93
	v_ashrrev_i32_e32 v37, 5, v36
	v_lshl_add_u32 v96, v37, 2, s93
	ds_add_rtn_u32 v37, v96, v208 offset:12288
	ds_add_rtn_u32 v39, v136, v208 offset:12288
	s_waitcnt lgkmcnt(0)
	ds_read_b32 v98, v2
	ds_read_b32 v97, v4
	ds_read_b32 v100, v6
	ds_read_b32 v99, v8
	s_waitcnt lgkmcnt(0)
	v_add_u32_e32 v101, v97, v98
	v_add3_u32 v129, v101, v100, v99
	ds_read_b32 v128, v10
	ds_read_b32 v101, v12
	s_waitcnt lgkmcnt(0)
	v_add3_u32 v153, v129, v128, v101
	ds_read_b32 v129, v14
	ds_read_b32 v154, v16
	s_waitcnt lgkmcnt(0)
	v_add3_u32 v153, v153, v129, v154
	v_cvt_f32_u32_e32 v154, v153
	s_nop 1
	v_add_f32_dpp v154, v154, v154 row_shr:1 row_mask:0xf bank_mask:0xf bound_ctrl:1
	s_nop 1
	v_add_f32_dpp v154, v154, v154 row_shr:2 row_mask:0xf bank_mask:0xf bound_ctrl:1
	s_nop 1
	v_add_f32_dpp v154, v154, v154 row_shr:4 row_mask:0xf bank_mask:0xf bound_ctrl:1
	s_nop 1
	v_add_f32_dpp v154, v154, v154 row_shr:8 row_mask:0xf bank_mask:0xf bound_ctrl:1
	s_nop 0
	v_readlane_b32 s44, v154, 15
	v_readlane_b32 s48, v154, 31
	v_readlane_b32 s45, v154, 47
	s_and_saveexec_b64 s[0:1], s[14:15]
	s_xor_b64 s[0:1], exec, s[0:1]
	s_cbranch_execz .LBB0_72
	s_and_saveexec_b64 s[52:53], s[12:13]
	s_xor_b64 s[64:65], exec, s[52:53]
	v_mov_b32_e32 v160, s44
	v_cndmask_b32_e32 v160, 0, v160, vcc
	s_andn2_saveexec_b64 s[64:65], s[64:65]
	v_mov_b32_e32 v160, s48
	v_add_f32_e32 v160, s44, v160
	s_or_b64 exec, exec, s[64:65]
.LBB0_72:
	s_andn2_saveexec_b64 s[0:1], s[0:1]
	v_mov_b32_e32 v160, s48
	v_add_f32_e32 v160, s44, v160
	v_add_f32_e32 v160, s45, v160
	s_or_b64 exec, exec, s[0:1]
	v_add_u32_e32 v96, 0x3000, v96
	v_cmp_ne_u32_e64 s[0:1], -1, v96
	v_readlane_b32 s44, v254, 10
	v_readlane_b32 s45, v254, 11
	v_cndmask_b32_e64 v162, 0, v96, s[0:1]
	v_add_f32_e32 v96, v154, v160
	v_cvt_u32_f32_e32 v96, v96
	v_mov_b32_e32 v161, s45
	v_cndmask_b32_e64 v163, 0, v161, s[0:1]
	v_add_u32_e32 v136, 0x3000, v136
	v_sub_u32_e32 v96, v96, v153
	ds_write_b32 v2, v96
	v_add_u32_e32 v96, v96, v98
	ds_write_b32 v4, v96
	v_add_u32_e32 v96, v96, v97
	ds_write_b32 v6, v96
	v_add_u32_e32 v96, v96, v100
	ds_write_b32 v8, v96
	v_add_u32_e32 v96, v96, v99
	ds_write_b32 v10, v96
	v_add_u32_e32 v96, v96, v128
	ds_write_b32 v12, v96
	v_add_u32_e32 v96, v96, v101
	ds_write_b32 v14, v96
	v_add_u32_e32 v96, v96, v129
	ds_write_b32 v16, v96
	s_waitcnt lgkmcnt(0)
	ds_read_b32 v96, v162
	v_cmp_ne_u32_e64 s[0:1], -1, v136
	s_or_b32 s66, s40, 6
	s_ashr_i32 s67, s66, 31
	v_cndmask_b32_e64 v165, 0, v161, s[0:1]
	v_cndmask_b32_e64 v164, 0, v136, s[0:1]
	s_lshl_b64 s[64:65], s[66:67], 11
	s_lshl_b64 s[0:1], s[66:67], 9
	s_waitcnt lgkmcnt(0)
	v_add_u32_e32 v100, v96, v37
	ds_read_b32 v37, v164
	s_waitcnt lgkmcnt(0)
	s_waitcnt lgkmcnt(0)
	v_add_u32_e32 v101, v37, v39
	v_ashrrev_i32_e32 v37, 31, v36
	v_lshl_add_u64 v[96:97], v[36:37], 3, s[28:29]
	v_ashrrev_i32_e32 v39, 31, v38
	s_waitcnt vmcnt(6)
	v_mov_b32_e32 v96, v240
	v_mov_b32_e32 v97, v241
	v_lshl_add_u64 v[98:99], v[38:39], 3, s[28:29]
	v_mov_b32_e32 v98, v242
	v_mov_b32_e32 v99, v243
	v_lshl_add_u32 v37, v100, 2, s93
	v_mul_f32_e32 v39, v94, v97
	ds_write2st64_b32 v37, v36, v39 offset0:30 offset1:32
	ds_write_b32 v37, v96 offset:8704
	v_lshl_add_u32 v36, v101, 2, s93
	v_mul_f32_e32 v37, v95, v99
	ds_write2st64_b32 v36, v38, v37 offset0:30 offset1:32
	ds_write_b32 v36, v98 offset:8704
	v_lshl_add_u64 v[94:95], v[18:19], 0, s[64:65]
	s_waitcnt vmcnt(0)
	v_mov_b32_e32 v36, v192
	v_mov_b32_e32 v37, v193
	v_mov_b32_e32 v38, v194
	v_mov_b32_e32 v39, v195
	s_nop 0
	v_mov_b32_e32 v94, v196
	v_mov_b32_e32 v95, v197
	v_mov_b32_e32 v96, v198
	v_mov_b32_e32 v97, v199
	v_lshlrev_b32_e32 v100, 16, v36
	v_lshlrev_b32_e32 v98, 16, v94
	v_and_b32_e32 v168, 0xffff0000, v94
	v_and_b32_e32 v162, 0xffff0000, v36
	v_lshlrev_b32_e32 v99, 16, v95
	v_and_b32_e32 v163, 0xffff0000, v95
	v_max3_f32 v36, |v98|, 0, |v168|
	v_lshlrev_b32_e32 v164, 16, v96
	v_and_b32_e32 v165, 0xffff0000, v96
	v_max3_f32 v36, v36, |v99|, |v163|
	v_lshlrev_b32_e32 v166, 16, v97
	v_and_b32_e32 v167, 0xffff0000, v97
	v_max3_f32 v36, v36, |v164|, |v165|
	v_max3_f32 v36, v36, |v166|, |v167|
	v_lshlrev_b32_e32 v101, 16, v37
	v_and_b32_e32 v136, 0xffff0000, v37
	v_max3_f32 v36, v36, |v100|, |v162|
	v_lshlrev_b32_e32 v153, 16, v38
	v_and_b32_e32 v154, 0xffff0000, v38
	v_max3_f32 v36, v36, |v101|, |v136|
	v_lshlrev_b32_e32 v160, 16, v39
	v_and_b32_e32 v161, 0xffff0000, v39
	v_max3_f32 v36, v36, |v153|, |v154|
	v_max3_f32 v36, v36, |v160|, |v161|
	v_lshl_or_b32 v94, v55, 2, s0
	v_mov_b32_e32 v95, s1
	v_mov_b32_dpp v37, v36 quad_perm:[1,0,3,2] row_mask:0xf bank_mask:0xf bound_ctrl:1
	v_max_f32_e32 v37, v37, v37
	v_max_f32_e32 v36, v36, v37
	v_or_b32_e32 v96, 0x100, v94
	v_mov_b32_e32 v97, s1
	v_mov_b32_dpp v37, v36 quad_perm:[2,3,0,1] row_mask:0xf bank_mask:0xf bound_ctrl:1
	v_max_f32_e32 v37, v37, v37
	v_max_f32_e32 v36, v36, v37
	v_lshl_add_u64 v[38:39], s[24:25], 0, v[96:97]
	v_mov_b32_e32 v38, v229
	v_mov_b32_dpp v37, v36 row_half_mirror row_mask:0xf bank_mask:0xf bound_ctrl:1
	v_max_f32_e32 v37, v37, v37
	v_max_f32_e32 v36, v36, v37
	v_lshl_add_u64 v[96:97], s[26:27], 0, v[96:97]
	s_nop 0
	v_mov_b32_dpp v37, v36 row_mirror row_mask:0xf bank_mask:0xf bound_ctrl:1
	v_max_f32_e32 v37, v37, v37
	v_max_f32_e32 v36, v36, v37
	s_nop 0
	v_readlane_b32 s72, v36, 0
	v_readlane_b32 s94, v36, 16
	v_readlane_b32 s60, v36, 32
	v_readlane_b32 s73, v36, 48
	v_lshl_add_u64 v[36:37], s[24:25], 0, v[94:95]
	v_mov_b32_e32 v36, v228
	v_lshl_add_u64 v[94:95], s[26:27], 0, v[94:95]
	v_mov_b32_e32 v94, v230
	s_waitcnt vmcnt(2)
	v_ashrrev_i32_e32 v39, 5, v38
	v_mov_b32_e32 v95, v231
	v_lshlrev_b32_e32 v244, 3, v36
	global_load_dwordx2 v[240:241], v244, s[28:29]
	v_lshlrev_b32_e32 v245, 3, v38
	global_load_dwordx2 v[242:243], v245, s[28:29]
	v_add_u32_e32 v238, 0x3800, v236
	global_load_dwordx4 v[200:203], v238, s[98:99] offset:16
	global_load_dwordx4 v[204:207], v238, s[98:99]
	v_add_u32_e32 v239, 0xe00, v237
	global_load_dword v232, v239, s[24:25]
	global_load_dword v233, v239, s[24:25] offset:256
	global_load_dword v234, v239, s[26:27]
	global_load_dword v235, v239, s[26:27] offset:256
	s_nop 0
	ds_write_b32 v20, v155
	ds_write_b32 v22, v155
	ds_write_b32 v24, v155
	ds_write_b32 v26, v155
	ds_write_b32 v28, v155
	ds_write_b32 v30, v155
	ds_write_b32 v32, v155
	ds_write_b32 v34, v155
	v_lshl_add_u32 v173, v39, 2, s93
	v_ashrrev_i32_e32 v37, 5, v36
	v_lshl_add_u32 v96, v37, 2, s93
	ds_add_rtn_u32 v37, v96, v208 offset:12288
	ds_add_rtn_u32 v39, v173, v208 offset:12288
	s_waitcnt lgkmcnt(0)
	ds_read_b32 v128, v2
	ds_read_b32 v97, v4
	ds_read_b32 v169, v6
	ds_read_b32 v129, v8
	s_waitcnt lgkmcnt(0)
	v_add_u32_e32 v170, v97, v128
	v_add3_u32 v172, v170, v169, v129
	ds_read_b32 v171, v10
	ds_read_b32 v170, v12
	s_waitcnt lgkmcnt(0)
	v_add3_u32 v174, v172, v171, v170
	ds_read_b32 v172, v14
	ds_read_b32 v175, v16
	s_waitcnt lgkmcnt(0)
	v_add3_u32 v174, v174, v172, v175
	v_cvt_f32_u32_e32 v175, v174
	s_nop 1
	v_add_f32_dpp v175, v175, v175 row_shr:1 row_mask:0xf bank_mask:0xf bound_ctrl:1
	s_nop 1
	v_add_f32_dpp v175, v175, v175 row_shr:2 row_mask:0xf bank_mask:0xf bound_ctrl:1
	s_nop 1
	v_add_f32_dpp v175, v175, v175 row_shr:4 row_mask:0xf bank_mask:0xf bound_ctrl:1
	s_nop 1
	v_add_f32_dpp v175, v175, v175 row_shr:8 row_mask:0xf bank_mask:0xf bound_ctrl:1
	s_nop 0
	v_readlane_b32 s44, v175, 15
	v_readlane_b32 s48, v175, 31
	v_readlane_b32 s45, v175, 47
	s_and_saveexec_b64 s[0:1], s[14:15]
	s_xor_b64 s[0:1], exec, s[0:1]
	s_cbranch_execz .LBB0_80
	s_and_saveexec_b64 s[52:53], s[12:13]
	s_xor_b64 s[68:69], exec, s[52:53]
	v_mov_b32_e32 v184, s44
	v_cndmask_b32_e32 v184, 0, v184, vcc
	s_andn2_saveexec_b64 s[68:69], s[68:69]
	v_mov_b32_e32 v184, s48
	v_add_f32_e32 v184, s44, v184
	s_or_b64 exec, exec, s[68:69]
.LBB0_80:
	s_andn2_saveexec_b64 s[0:1], s[0:1]
	v_mov_b32_e32 v184, s48
	v_add_f32_e32 v184, s44, v184
	v_add_f32_e32 v184, s45, v184
	s_or_b64 exec, exec, s[0:1]
	v_add_u32_e32 v96, 0x3000, v96
	v_cmp_ne_u32_e64 s[0:1], -1, v96
	v_readlane_b32 s44, v254, 10
	v_readlane_b32 s45, v254, 11
	v_cndmask_b32_e64 v186, 0, v96, s[0:1]
	v_add_f32_e32 v96, v175, v184
	v_cvt_u32_f32_e32 v96, v96
	v_mov_b32_e32 v185, s45
	v_cndmask_b32_e64 v187, 0, v185, s[0:1]
	v_add_u32_e32 v173, 0x3000, v173
	v_sub_u32_e32 v96, v96, v174
	ds_write_b32 v2, v96
	v_add_u32_e32 v96, v96, v128
	ds_write_b32 v4, v96
	v_add_u32_e32 v96, v96, v97
	ds_write_b32 v6, v96
	v_add_u32_e32 v96, v96, v169
	ds_write_b32 v8, v96
	v_add_u32_e32 v96, v96, v129
	ds_write_b32 v10, v96
	v_add_u32_e32 v96, v96, v171
	ds_write_b32 v12, v96
	v_add_u32_e32 v96, v96, v170
	ds_write_b32 v14, v96
	v_add_u32_e32 v96, v96, v172
	ds_write_b32 v16, v96
	s_waitcnt lgkmcnt(0)
	ds_read_b32 v96, v186
	v_cmp_ne_u32_e64 s[0:1], -1, v173
	s_or_b32 s70, s40, 7
	s_ashr_i32 s71, s70, 31
	v_cndmask_b32_e64 v189, 0, v185, s[0:1]
	v_cndmask_b32_e64 v188, 0, v173, s[0:1]
	s_lshl_b64 s[68:69], s[70:71], 11
	v_lshl_add_u64 v[18:19], v[18:19], 0, s[68:69]
	s_lshl_b64 s[0:1], s[70:71], 9
	s_waitcnt lgkmcnt(0)
	v_add_u32_e32 v169, v96, v37
	ds_read_b32 v37, v188
	s_waitcnt lgkmcnt(0)
	s_waitcnt lgkmcnt(0)
	v_add_u32_e32 v170, v37, v39
	v_ashrrev_i32_e32 v37, 31, v36
	v_lshl_add_u64 v[96:97], v[36:37], 3, s[28:29]
	v_ashrrev_i32_e32 v39, 31, v38
	s_waitcnt vmcnt(6)
	v_mov_b32_e32 v96, v240
	v_mov_b32_e32 v97, v241
	v_lshl_add_u64 v[128:129], v[38:39], 3, s[28:29]
	v_mov_b32_e32 v128, v242
	v_mov_b32_e32 v129, v243
	v_lshl_add_u32 v37, v169, 2, s93
	v_mul_f32_e32 v39, v94, v97
	ds_write2st64_b32 v37, v36, v39 offset0:36 offset1:38
	ds_write_b32 v37, v96 offset:10240
	v_lshl_add_u32 v36, v170, 2, s93
	v_mul_f32_e32 v37, v95, v129
	ds_write2st64_b32 v36, v38, v37 offset0:36 offset1:38
	ds_write_b32 v36, v128 offset:10240
	s_waitcnt vmcnt(0)
	v_mov_b32_e32 v36, v200
	v_mov_b32_e32 v37, v201
	v_mov_b32_e32 v38, v202
	v_mov_b32_e32 v39, v203
	v_mov_b32_e32 v186, v204
	v_mov_b32_e32 v187, v205
	v_mov_b32_e32 v188, v206
	v_mov_b32_e32 v189, v207
	v_lshlrev_b32_e32 v96, 16, v36
	v_lshlrev_b32_e32 v94, 16, v186
	v_and_b32_e32 v186, 0xffff0000, v186
	v_lshlrev_b32_e32 v184, 16, v187
	v_and_b32_e32 v185, 0xffff0000, v187
	v_max3_f32 v18, |v94|, 0, |v186|
	v_lshlrev_b32_e32 v95, 16, v188
	v_and_b32_e32 v175, 0xffff0000, v188
	v_max3_f32 v18, v18, |v184|, |v185|
	v_lshlrev_b32_e32 v173, 16, v189
	v_and_b32_e32 v174, 0xffff0000, v189
	v_max3_f32 v18, v18, |v95|, |v175|
	v_and_b32_e32 v170, 0xffff0000, v36
	v_max3_f32 v18, v18, |v173|, |v174|
	v_lshlrev_b32_e32 v171, 16, v37
	v_and_b32_e32 v172, 0xffff0000, v37
	v_max3_f32 v18, v18, |v96|, |v170|
	v_lshlrev_b32_e32 v97, 16, v38
	v_and_b32_e32 v169, 0xffff0000, v38
	v_max3_f32 v18, v18, |v171|, |v172|
	v_lshlrev_b32_e32 v37, 16, v39
	v_and_b32_e32 v129, 0xffff0000, v39
	v_max3_f32 v18, v18, |v97|, |v169|
	v_max3_f32 v18, v18, |v37|, |v129|
	v_lshl_or_b32 v38, v55, 2, s0
	v_mov_b32_e32 v39, s1
	v_mov_b32_dpp v19, v18 quad_perm:[1,0,3,2] row_mask:0xf bank_mask:0xf bound_ctrl:1
	v_max_f32_e32 v19, v19, v19
	v_max_f32_e32 v18, v18, v19
	v_or_b32_e32 v188, 0x100, v38
	v_mov_b32_e32 v189, s1
	v_mov_b32_dpp v19, v18 quad_perm:[2,3,0,1] row_mask:0xf bank_mask:0xf bound_ctrl:1
	v_max_f32_e32 v19, v19, v19
	v_max_f32_e32 v18, v18, v19
	v_lshl_add_u64 v[190:191], s[24:25], 0, v[188:189]
	v_mov_b32_e32 v36, v233
	v_mov_b32_dpp v19, v18 row_half_mirror row_mask:0xf bank_mask:0xf bound_ctrl:1
	v_max_f32_e32 v19, v19, v19
	v_max_f32_e32 v18, v18, v19
	v_lshl_add_u64 v[188:189], s[26:27], 0, v[188:189]
	s_nop 0
	v_mov_b32_dpp v19, v18 row_mirror row_mask:0xf bank_mask:0xf bound_ctrl:1
	v_max_f32_e32 v19, v19, v19
	v_max_f32_e32 v18, v18, v19
	s_nop 0
	v_readlane_b32 s44, v18, 0
	v_readlane_b32 s48, v18, 16
	v_readlane_b32 s95, v18, 32
	v_readlane_b32 s45, v18, 48
	v_lshl_add_u64 v[18:19], s[24:25], 0, v[38:39]
	v_mov_b32_e32 v18, v232
	v_lshl_add_u64 v[38:39], s[26:27], 0, v[38:39]
	v_mov_b32_e32 v38, v234
	s_waitcnt vmcnt(1)
	v_ashrrev_i32_e32 v19, 5, v18
	v_mov_b32_e32 v39, v235
	s_nop 0
	ds_write_b32 v20, v155
	s_waitcnt vmcnt(0)
	ds_write_b32 v22, v155
	ds_write_b32 v24, v155
	ds_write_b32 v26, v155
	ds_write_b32 v28, v155
	ds_write_b32 v30, v155
	ds_write_b32 v32, v155
	ds_write_b32 v34, v155
	v_lshl_add_u32 v20, v19, 2, s93
	v_ashrrev_i32_e32 v21, 5, v36
	ds_add_rtn_u32 v19, v20, v208 offset:12288
	v_lshl_add_u32 v21, v21, 2, s93
	ds_add_rtn_u32 v24, v21, v208 offset:12288
	s_waitcnt lgkmcnt(0)
	ds_read_b32 v26, v2
	ds_read_b32 v25, v4
	ds_read_b32 v28, v6
	ds_read_b32 v27, v8
	ds_read_b32 v30, v10
	ds_read_b32 v29, v12
	ds_read_b32 v31, v14
	ds_read_b32 v23, v16
	s_waitcnt lgkmcnt(0)
	v_add_u32_e32 v22, v25, v26
	v_add3_u32 v22, v22, v28, v27
	v_add3_u32 v22, v22, v30, v29
	v_add3_u32 v32, v22, v31, v23
	v_cvt_f32_u32_e32 v22, v32
	s_nop 1
	v_add_f32_dpp v22, v22, v22 row_shr:1 row_mask:0xf bank_mask:0xf bound_ctrl:1
	s_nop 1
	v_add_f32_dpp v22, v22, v22 row_shr:2 row_mask:0xf bank_mask:0xf bound_ctrl:1
	s_nop 1
	v_add_f32_dpp v22, v22, v22 row_shr:4 row_mask:0xf bank_mask:0xf bound_ctrl:1
	s_nop 1
	v_add_f32_dpp v33, v22, v22 row_shr:8 row_mask:0xf bank_mask:0xf bound_ctrl:1
	s_nop 0
	v_readlane_b32 s49, v33, 15
	v_readlane_b32 s53, v33, 31
	v_readlane_b32 s52, v33, 47
	s_and_saveexec_b64 s[0:1], s[14:15]
	s_xor_b64 s[0:1], exec, s[0:1]
	s_cbranch_execz .LBB0_88
	s_mov_b32 s34, s57
	s_and_saveexec_b64 s[14:15], s[12:13]
	s_xor_b64 s[12:13], exec, s[14:15]
	v_mov_b32_e32 v22, s49
	v_cndmask_b32_e32 v34, 0, v22, vcc
	s_andn2_saveexec_b64 s[12:13], s[12:13]
	v_mov_b32_e32 v22, s53
	v_add_f32_e32 v34, s49, v22
	s_or_b64 exec, exec, s[12:13]
	s_mov_b32 s56, 0xf800000
	s_mov_b32 s57, s34
